# speedup vs baseline: 1.0295x; 1.0085x over previous
; #define LAS __attribute__((address_space(3)))
; __device__ __forceinline__ unsigned cvt_pk_bf16(float lo, float hi) { return __builtin_bit_cast(unsigned, __builtin_amdgcn_cvt_pkrtz(lo, hi)); }
; #define bx (opaque_bx())
; __device__ __forceinline__ void phase_prep(int wid_s, const Args& a, unsigned char* shm) {
;     ...
;         while (t < PT_TOTAL) {
;             { const int w = tid >> 6, s4 = tid & 63;
; #pragma unroll
;               for (int q = 0; q < 4; ++q) { const u32x4 pc = {cvt_pk_bf16(r[0][q], r[1][q]), cvt_pk_bf16(r[2][q], r[3][q]), cvt_pk_bf16(r[4][q], r[5][q]), cvt_pk_bf16(r[6][q], r[7][q])};
;                   *(LAS u32x4*)(Lp + (4 * s4 + q) * 36 + 4 * w) = pc; } }
;             __syncthreads();
;             const PrepTask C = T; ++j; const int tn = ((j >> 2) * G + bx) * 4 + (j & 3);
;             if (tn < PT_TOTAL) { T = prep_decode(a, tn); prep_load(T, r, tid); }
.LBB0_42:
	s_lshr_b32 s9, s37, 2
	s_mul_i32 s9, s9, s76
	v_readlane_b32 s12, v253, 0
	s_add_i32 s9, s9, s12
	s_cmpk_lt_u32 s9, 0x29c
	s_cbranch_scc1 .Lrm_done
	s_sub_u32 s98, s9, 0x29c
	s_movk_i32 s99, 0x29c
	s_cmpk_lt_u32 s98, 0x15c
	s_cbranch_scc1 .Lrm_q
	s_sub_u32 s98, s98, 0x15c
	s_addk_i32 s99, 0x29c
	s_cmpk_lt_u32 s98, 0x15c
	s_cbranch_scc1 .Lrm_q
	s_sub_u32 s98, s98, 0x15c
	s_addk_i32 s99, 0x29c
	s_cmpk_lt_u32 s98, 0x15c
	s_cbranch_scc1 .Lrm_q
	s_sub_u32 s98, s98, 0x15c
	s_addk_i32 s99, 0x29c
.Lrm_q:
	s_cmpk_lt_u32 s98, 0x90
	s_cbranch_scc1 .Lrm_add
	s_addk_i32 s98, 0x140

; __device__ __forceinline__ int opaque_tid(int wid_s) { int l = __builtin_amdgcn_mbcnt_hi(~0u, __builtin_amdgcn_mbcnt_lo(~0u, 0u)); asm volatile("" : "+v"(l)); return (wid_s << 6) | l; }
; __device__ __forceinline__ void phase_ssm1(int wid_s, int vb, int nvb, unsigned char* shm, const float* US, const float* SSA, const float* SSB, float* FIN) {
;     const int tid = opaque_tid(wid_s), lane = tid & 63, wid = tid >> 6, fr = lane & 15, fq = lane >> 4;
;     float* X = (float*)shm + wid * (16 * 132);
;     for (int item = vb * 8 + wid; item < BATCH * 32 * NCH; item += nvb * 8) {
;         const int ch = item & (NCH - 1), g = (item / NCH) & 31, b = item / (NCH * 32);
;         SsmProj P; ssm_proj_load(P, SSB, g, fr, fq);
;         const f32x4 A = *(const f32x4*)(SSA + ((size_t)g * 64 + lane) * 4);
;         float sr = 0.f, si = 0.f;
;         u32x4 uw = ssm_u_load(US, (size_t)b * SEQ + ch * LCH, g, fr, fq);
.LBB0_292:
	v_readlane_b32 s0, v253, 0
	v_readlane_b32 s1, v253, 1
	s_mov_b32 s2, s0
	s_waitcnt lgkmcnt(0)
	s_barrier
	s_mov_b64 s[0:1], s[72:73]
	s_mov_b64 s[6:7], s[72:73]
	v_mov_b32_e32 v4, v240
	v_readlane_b32 s3, v253, 4
	s_lshl_b32 s2, s2, 3
	s_addk_i32 s2, 0xfc00
	v_or_b32_e32 v0, s3, v4
	v_ashrrev_i32_e32 v0, 6, v0
	v_add_u32_e32 v1, s2, v0
	s_movk_i32 s2, 0x1000
	v_cmp_gt_u32_e32 vcc, s2, v1
	s_and_saveexec_b64 s[2:3], vcc
	s_cbranch_execz .LBB0_321
	s_add_u32 s4, s0, 0x21600000
	s_movk_i32 s0, 0x2100
	s_waitcnt vmcnt(0)
	v_lshlrev_b32_e32 v6, 6, v4
	v_readlane_b32 s8, v254, 5
	v_mul_lo_u32 v0, v0, s0
	v_bfe_u32 v5, v4, 4, 2
	v_and_b32_e32 v6, 64, v6
	v_mov_b32_e32 v7, v2
	v_readlane_b32 s9, v254, 6
	v_add_u32_e32 v9, 0, v0
	v_and_b32_e32 v0, 15, v4
	v_lshl_add_u64 v[6:7], s[8:9], 0, v[6:7]
	v_lshlrev_b32_e32 v8, 3, v5
	v_lshlrev_b32_e32 v10, 5, v5
	v_mov_b32_e32 v11, v2
	v_mul_u32_u24_e32 v5, 0x210, v5
	v_lshl_add_u64 v[40:41], v[6:7], 0, v[10:11]
	v_lshlrev_b32_e32 v7, 2, v0
	v_lshlrev_b32_e32 v5, 2, v5
	s_addc_u32 s5, s1, 0
	v_and_b32_e32 v12, 63, v4
	v_lshlrev_b32_e32 v3, 4, v4
	v_add3_u32 v61, v9, v7, v5
	v_and_b32_e32 v4, 48, v4
	v_mov_b32_e32 v5, v2
	v_lshl_add_u64 v[42:43], s[4:5], 0, v[4:5]
	v_lshlrev_b32_e32 v4, 3, v12
	v_lshlrev_b32_e32 v6, 2, v12
	v_add_u32_e32 v62, v9, v4
	v_lshl_add_u64 v[4:5], s[6:7], 0, v[4:5]
	s_mov_b64 s[6:7], 0x2bb76000
	v_cmp_gt_u32_e64 s[0:1], 32, v12
	v_and_b32_e32 v3, 0xe0, v3
	v_lshl_add_u64 v[44:45], v[4:5], 0, s[6:7]
	s_mov_b64 s[6:7], 0
	v_lshlrev_b32_e32 v63, 2, v6
	v_lshlrev_b32_e32 v46, 1, v8

; __device__ __forceinline__ void wave_lds_fence() { asm volatile("s_waitcnt lgkmcnt(0)" ::: "memory"); __builtin_amdgcn_wave_barrier(); }
; __device__ __forceinline__ void phase_ssm1(int wid_s, int vb, int nvb, unsigned char* shm, const float* US, const float* SSA, const float* SSB, float* FIN) {
;     ...
;         for (int sub = 0; sub < 4; ++sub) {
;             wave_lds_fence();
;             ssm_proj16(P, uw, X, fr, fq);
;             if (sub < 3) uw = ssm_u_load(US, (size_t)b * SEQ + ch * LCH + (sub + 1) * 16, g, fr, fq);
;             wave_lds_fence();
; #pragma unroll 4
;             for (int t16 = 0; t16 < 16; ++t16) { const f32x2 x = *(const f32x2*)(X + t16 * 132 + 2 * lane);
;                 const float nr = A[0] * sr - A[1] * si + x.x, ni = A[0] * si + A[1] * sr + x.y; sr = nr; si = ni; }
;         }
;         *(f32x2*)(FIN + ((size_t)((b * 32 + g) * NCH + ch) * 64 + lane) * 2) = (f32x2){sr, si};
;     }
.LBB0_319:
	v_add_u32_e32 v12, s8, v62
	ds_read2_b64 v[4:7], v12 offset1:66
	v_pk_mul_f32 v[8:9], v[54:55], v[56:57] op_sel:[0,1]
	s_addk_i32 s8, 0x840
	v_pk_fma_f32 v[10:11], v[48:49], v[56:57], v[8:9] neg_lo:[0,0,1] neg_hi:[0,0,1]
	v_pk_fma_f32 v[8:9], v[48:49], v[56:57], v[8:9] op_sel_hi:[1,0,1]
	s_cmpk_lg_i32 s8, 0x2100
	v_mov_b32_e32 v11, v9
	s_waitcnt lgkmcnt(0)
	v_pk_add_f32 v[4:5], v[10:11], v[4:5]
	s_nop 0
	v_pk_mul_f32 v[8:9], v[54:55], v[4:5] op_sel:[0,1]
	s_nop 0
	v_pk_fma_f32 v[10:11], v[48:49], v[4:5], v[8:9] neg_lo:[0,0,1] neg_hi:[0,0,1]
	v_pk_fma_f32 v[4:5], v[48:49], v[4:5], v[8:9] op_sel_hi:[1,0,1]
	s_nop 0
	v_mov_b32_e32 v11, v5
	v_pk_add_f32 v[8:9], v[10:11], v[6:7]
	ds_read2_b64 v[4:7], v12 offset0:132 offset1:198
	v_pk_mul_f32 v[10:11], v[54:55], v[8:9] op_sel:[0,1]
	s_nop 0
	v_pk_fma_f32 v[12:13], v[48:49], v[8:9], v[10:11] neg_lo:[0,0,1] neg_hi:[0,0,1]
	v_pk_fma_f32 v[8:9], v[48:49], v[8:9], v[10:11] op_sel_hi:[1,0,1]
	s_nop 0
	v_mov_b32_e32 v13, v9
	s_waitcnt lgkmcnt(0)
	v_pk_add_f32 v[4:5], v[12:13], v[4:5]
	s_nop 0
	v_pk_mul_f32 v[8:9], v[54:55], v[4:5] op_sel:[0,1]
	s_nop 0
	v_pk_fma_f32 v[10:11], v[48:49], v[4:5], v[8:9] neg_lo:[0,0,1] neg_hi:[0,0,1]
	v_pk_fma_f32 v[4:5], v[48:49], v[4:5], v[8:9] op_sel_hi:[1,0,1]
	s_nop 0
	v_mov_b32_e32 v11, v5
	v_pk_add_f32 v[56:57], v[10:11], v[6:7]
	s_cbranch_scc1 .LBB0_319
	v_lshlrev_b32_e32 v4, 10, v50
	v_or3_b32 v4, v52, v4, v64
	s_movk_i32 s8, 0x400
	v_ashrrev_i32_e32 v5, 31, v4
	v_lshlrev_b64 v[4:5], 9, v[4:5]
	v_add_u32_e32 v1, s8, v1
	s_movk_i32 s8, 0xfff
	v_cmp_lt_i32_e32 vcc, s8, v1
	v_lshl_add_u64 v[4:5], v[44:45], 0, v[4:5]
	s_or_b64 s[6:7], vcc, s[6:7]
	flat_store_dwordx2 v[4:5], v[56:57]
	s_andn2_b64 exec, exec, s[6:7]
	s_cbranch_execnz .LBB0_294

; #define LAS __attribute__((address_space(3)))
; __device__ __forceinline__ int opaque_tid(int wid_s) { int l = __builtin_amdgcn_mbcnt_hi(~0u, __builtin_amdgcn_mbcnt_lo(~0u, 0u)); asm volatile("" : "+v"(l)); return (wid_s << 6) | l; }
; __device__ __forceinline__ unsigned cvt_pk_bf16(float lo, float hi) { return __builtin_bit_cast(unsigned, __builtin_amdgcn_cvt_pkrtz(lo, hi)); }
; __host__ __device__ __forceinline__ int in_logical_pn(int j) { return (j < 6) ? j : (j < 8 ? j + 2 : j - 2); }
; #define bx (opaque_bx())
; __device__ __forceinline__ void prep_load(const PrepTask& T, f32x4 (&r)[8], int tid) {
;     const int w = tid >> 6, s4 = tid & 63; const int col = colmap(T.kind, T.kind == KIND_IN ? in_logical_pn(T.pn) : T.pn, 4 * s4);
; #pragma unroll
;     for (int i = 0; i < 8; ++i) r[i] = __builtin_nontemporal_load((const f32x4*)(T.src + (size_t)(T.k0 + 8 * w + i) * T.Nnat + col));
; }
; __device__ __forceinline__ void phase_prep(int wid_s, const Args& a, unsigned char* shm) {
;     const int tid = opaque_tid(wid_s), G = gridDim.x, bx = blockIdx.x;
;     float* Ts = (float*)shm;
;     {
;         LAS unsigned* Lp = (LAS unsigned*)shm;
;         f32x4 r[8]; int j = 0; int t = bx * 4; PrepTask T;
;         if (t < PT_TOTAL) { T = prep_decode(a, t); prep_load(T, r, tid); }
;         while (t < PT_TOTAL) {
;             { const int w = tid >> 6, s4 = tid & 63;
; #pragma unroll
;               for (int q = 0; q < 4; ++q) { const u32x4 pc = {cvt_pk_bf16(r[0][q], r[1][q]), cvt_pk_bf16(r[2][q], r[3][q]), cvt_pk_bf16(r[4][q], r[5][q]), cvt_pk_bf16(r[6][q], r[7][q])};
;                   *(LAS u32x4*)(Lp + (4 * s4 + q) * 36 + 4 * w) = pc; } }
.LBB0_808:
	s_waitcnt vmcnt(0)
	s_barrier
	s_cmp_gt_u32 s86, 2
	s_cbranch_scc1 .Ltp_done
	v_readlane_b32 s5, v253, 0
	s_sub_u32 s5, s5, 0x60
	s_cbranch_scc1 .Ltp_done
	s_cmp_gt_u32 s5, 0x9f
	s_cbranch_scc1 .Ltp_done
	s_mov_b64 exec, -1
	s_lshr_b32 s6, s5, 2
	s_and_b32 s5, s5, 3
	s_add_i32 s7, s86, 1
	s_mul_i32 s8, s7, 0x5600000
	s_mul_i32 s9, s5, 0x1580000
	s_add_u32 s8, s8, s9
	s_lshl_b32 s9, s6, 9
	s_add_u32 s8, s8, s9
	v_readlane_b32 s0, v253, 23
	v_readlane_b32 s1, v253, 24
	s_add_u32 s0, s0, s8
	s_addc_u32 s1, s1, 0
	s_mul_i32 s8, s7, 0x2b00000
	s_add_u32 s8, s8, 0x4800000
	s_lshl_b32 s9, s6, 20
	s_add_u32 s8, s8, s9
	s_lshl_b32 s9, s5, 10
	s_add_u32 s8, s8, s9
	s_add_u32 s2, s72, s8
	s_addc_u32 s3, s73, 0
	v_mbcnt_lo_u32_b32 v114, -1, 0
	v_mbcnt_hi_u32_b32 v114, -1, v114
	v_readlane_b32 s5, v253, 37
	s_lshr_b32 s6, s5, 6
	v_bfe_u32 v115, v114, 5, 1
	v_mul_u32_u24_e32 v115, 0x5600, v115
	v_bfe_u32 v116, v114, 3, 2
	v_lshl_add_u32 v115, v116, 7, v115
	v_and_b32_e32 v116, 3, v114
	v_lshl_add_u32 v115, v116, 5, v115
	v_bfe_u32 v116, v114, 2, 1
	v_lshl_add_u32 v115, v116, 4, v115
	s_mul_i32 s7, s6, 0x56000
	v_add_u32_e32 v100, s7, v115
	v_add_u32_e32 v101, 0xac00, v100
	v_add_u32_e32 v102, 0xac00, v101
	v_add_u32_e32 v103, 0xac00, v102
	v_add_u32_e32 v104, 0xac00, v103
	v_add_u32_e32 v105, 0xac00, v104
	v_add_u32_e32 v106, 0xac00, v105
	v_add_u32_e32 v107, 0xac00, v106
	v_mul_u32_u24_e32 v108, 0x240, v114
	s_lshl_b32 s7, s6, 4
	v_add_u32_e32 v108, s7, v108
	v_lshrrev_b32_e32 v116, 3, v114
	s_lshl_b32 s7, s6, 3
	v_add_u32_e32 v116, s7, v116
	v_and_b32_e32 v117, 7, v114
	v_lshlrev_b32_e32 v117, 4, v117
	v_mul_u32_u24_e32 v109, 0x90, v116
	v_add_u32_e32 v109, v109, v117
	v_lshl_add_u32 v110, v116, 12, v117
	v_add_u32_e32 v111, 0x40000, v110
	v_add_u32_e32 v112, 0x40000, v111
	v_add_u32_e32 v113, 0x40000, v112
	global_load_dwordx4 v[4:7], v100, s[0:1] nt
	global_load_dwordx4 v[8:11], v101, s[0:1] nt
	global_load_dwordx4 v[12:15], v102, s[0:1] nt
	global_load_dwordx4 v[16:19], v103, s[0:1] nt
	global_load_dwordx4 v[20:23], v104, s[0:1] nt
	global_load_dwordx4 v[24:27], v105, s[0:1] nt
	global_load_dwordx4 v[28:31], v106, s[0:1] nt
	global_load_dwordx4 v[32:35], v107, s[0:1] nt
	s_add_u32 s0, s0, 0x2b0000
	s_addc_u32 s1, s1, 0
	global_load_dwordx4 v[36:39], v100, s[0:1] nt
	global_load_dwordx4 v[40:43], v101, s[0:1] nt
	global_load_dwordx4 v[44:47], v102, s[0:1] nt
	global_load_dwordx4 v[48:51], v103, s[0:1] nt
	global_load_dwordx4 v[52:55], v104, s[0:1] nt
	global_load_dwordx4 v[56:59], v105, s[0:1] nt
	global_load_dwordx4 v[60:63], v106, s[0:1] nt
	global_load_dwordx4 v[64:67], v107, s[0:1] nt
	s_add_u32 s0, s0, 0x2b0000
	s_addc_u32 s1, s1, 0
	s_mov_b32 s4, 3
	s_waitcnt vmcnt(8)
; #define LAS __attribute__((address_space(3)))
; __device__ __forceinline__ unsigned cvt_pk_bf16(float lo, float hi) { return __builtin_bit_cast(unsigned, __builtin_amdgcn_cvt_pkrtz(lo, hi)); }
; #define bx (opaque_bx())
; __device__ __forceinline__ void phase_prep(int wid_s, const Args& a, unsigned char* shm) {
;     ...
;             { const int w = tid >> 6, s4 = tid & 63;
; #pragma unroll
;               for (int q = 0; q < 4; ++q) { const u32x4 pc = {cvt_pk_bf16(r[0][q], r[1][q]), cvt_pk_bf16(r[2][q], r[3][q]), cvt_pk_bf16(r[4][q], r[5][q]), cvt_pk_bf16(r[6][q], r[7][q])};
;                   *(LAS u32x4*)(Lp + (4 * s4 + q) * 36 + 4 * w) = pc; } }
;             __syncthreads();
;             const PrepTask C = T; ++j; const int tn = ((j >> 2) * G + bx) * 4 + (j & 3);
;             if (tn < PT_TOTAL) { T = prep_decode(a, tn); prep_load(T, r, tid); }
; #pragma unroll
;             for (int q = 0; q < 4; ++q) { const int row = q * 64 + (tid >> 3), pc = tid & 7;
;                 const u32x4 v = *(const LAS u32x4*)(Lp + row * 36 + 4 * pc);
;                 *(u32x4*)(C.dst + (size_t)(256 * C.pn + row) * C.K + C.k0 + 8 * pc) = v; }
;             __syncthreads();
;             t = tn;
.Ltp_loop:
	v_cvt_pkrtz_f16_f32 v68, v4, v8
	v_cvt_pkrtz_f16_f32 v69, v12, v16
	v_cvt_pkrtz_f16_f32 v70, v20, v24
	v_cvt_pkrtz_f16_f32 v71, v28, v32
	ds_write_b128 v108, v[68:71] offset:0
	v_cvt_pkrtz_f16_f32 v72, v5, v9
	v_cvt_pkrtz_f16_f32 v73, v13, v17
	v_cvt_pkrtz_f16_f32 v74, v21, v25
	v_cvt_pkrtz_f16_f32 v75, v29, v33
	ds_write_b128 v108, v[72:75] offset:144
	v_cvt_pkrtz_f16_f32 v76, v6, v10
	v_cvt_pkrtz_f16_f32 v77, v14, v18
	v_cvt_pkrtz_f16_f32 v78, v22, v26
	v_cvt_pkrtz_f16_f32 v79, v30, v34
	ds_write_b128 v108, v[76:79] offset:288
	v_cvt_pkrtz_f16_f32 v80, v7, v11
	v_cvt_pkrtz_f16_f32 v81, v15, v19
	v_cvt_pkrtz_f16_f32 v82, v23, v27
	v_cvt_pkrtz_f16_f32 v83, v31, v35
	ds_write_b128 v108, v[80:83] offset:432
	s_waitcnt lgkmcnt(0)
	s_barrier
	ds_read_b128 v[84:87], v109 offset:0
	ds_read_b128 v[88:91], v109 offset:9216
	ds_read_b128 v[92:95], v109 offset:18432
	ds_read_b128 v[96:99], v109 offset:27648
	s_waitcnt lgkmcnt(3)
	global_store_dwordx4 v110, v[84:87], s[2:3] nt
	s_waitcnt lgkmcnt(2)
	global_store_dwordx4 v111, v[88:91], s[2:3] nt
	s_waitcnt lgkmcnt(1)
	global_store_dwordx4 v112, v[92:95], s[2:3] nt
	s_waitcnt lgkmcnt(0)
	global_store_dwordx4 v113, v[96:99], s[2:3] nt
	s_add_u32 s2, s2, 0x80
	s_addc_u32 s3, s3, 0
	s_cmp_eq_u32 s4, 0
	s_cbranch_scc1 .Ltp_last
	global_load_dwordx4 v[4:7], v100, s[0:1] nt
	global_load_dwordx4 v[8:11], v101, s[0:1] nt
	global_load_dwordx4 v[12:15], v102, s[0:1] nt
	global_load_dwordx4 v[16:19], v103, s[0:1] nt
	global_load_dwordx4 v[20:23], v104, s[0:1] nt
	global_load_dwordx4 v[24:27], v105, s[0:1] nt
	global_load_dwordx4 v[28:31], v106, s[0:1] nt
	global_load_dwordx4 v[32:35], v107, s[0:1] nt
	s_add_u32 s0, s0, 0x2b0000
	s_addc_u32 s1, s1, 0
	s_waitcnt vmcnt(12)
	v_cvt_pkrtz_f16_f32 v68, v36, v40
	v_cvt_pkrtz_f16_f32 v69, v44, v48
	v_cvt_pkrtz_f16_f32 v70, v52, v56
	v_cvt_pkrtz_f16_f32 v71, v60, v64
	ds_write_b128 v108, v[68:71] offset:36864
	v_cvt_pkrtz_f16_f32 v72, v37, v41
	v_cvt_pkrtz_f16_f32 v73, v45, v49
	v_cvt_pkrtz_f16_f32 v74, v53, v57
	v_cvt_pkrtz_f16_f32 v75, v61, v65
	ds_write_b128 v108, v[72:75] offset:37008
	v_cvt_pkrtz_f16_f32 v76, v38, v42
	v_cvt_pkrtz_f16_f32 v77, v46, v50
	v_cvt_pkrtz_f16_f32 v78, v54, v58
	v_cvt_pkrtz_f16_f32 v79, v62, v66
	ds_write_b128 v108, v[76:79] offset:37152
	v_cvt_pkrtz_f16_f32 v80, v39, v43
	v_cvt_pkrtz_f16_f32 v81, v47, v51
	v_cvt_pkrtz_f16_f32 v82, v55, v59
	v_cvt_pkrtz_f16_f32 v83, v63, v67
	ds_write_b128 v108, v[80:83] offset:37296
	s_waitcnt lgkmcnt(0)
	s_barrier
	ds_read_b128 v[84:87], v109 offset:36864
	ds_read_b128 v[88:91], v109 offset:46080
	ds_read_b128 v[92:95], v109 offset:55296
	ds_read_b128 v[96:99], v109 offset:64512
	s_waitcnt lgkmcnt(3)
	global_store_dwordx4 v110, v[84:87], s[2:3] nt
	s_waitcnt lgkmcnt(2)
	global_store_dwordx4 v111, v[88:91], s[2:3] nt
	s_waitcnt lgkmcnt(1)
	global_store_dwordx4 v112, v[92:95], s[2:3] nt
	s_waitcnt lgkmcnt(0)
	global_store_dwordx4 v113, v[96:99], s[2:3] nt
	s_add_u32 s2, s2, 0x80
	s_addc_u32 s3, s3, 0
	global_load_dwordx4 v[36:39], v100, s[0:1] nt
	global_load_dwordx4 v[40:43], v101, s[0:1] nt
	global_load_dwordx4 v[44:47], v102, s[0:1] nt
	global_load_dwordx4 v[48:51], v103, s[0:1] nt
	global_load_dwordx4 v[52:55], v104, s[0:1] nt
	global_load_dwordx4 v[56:59], v105, s[0:1] nt
	global_load_dwordx4 v[60:63], v106, s[0:1] nt
	global_load_dwordx4 v[64:67], v107, s[0:1] nt
	s_add_u32 s0, s0, 0x2b0000
	s_addc_u32 s1, s1, 0
	s_sub_u32 s4, s4, 1
	s_waitcnt vmcnt(12)
	s_branch .Ltp_loop
.Ltp_last:
	s_waitcnt vmcnt(4)
	v_cvt_pkrtz_f16_f32 v68, v36, v40
	v_cvt_pkrtz_f16_f32 v69, v44, v48
	v_cvt_pkrtz_f16_f32 v70, v52, v56
	v_cvt_pkrtz_f16_f32 v71, v60, v64
	ds_write_b128 v108, v[68:71] offset:36864
	v_cvt_pkrtz_f16_f32 v72, v37, v41
	v_cvt_pkrtz_f16_f32 v73, v45, v49
	v_cvt_pkrtz_f16_f32 v74, v53, v57
	v_cvt_pkrtz_f16_f32 v75, v61, v65
	ds_write_b128 v108, v[72:75] offset:37008
	v_cvt_pkrtz_f16_f32 v76, v38, v42
	v_cvt_pkrtz_f16_f32 v77, v46, v50
	v_cvt_pkrtz_f16_f32 v78, v54, v58
	v_cvt_pkrtz_f16_f32 v79, v62, v66
	ds_write_b128 v108, v[76:79] offset:37152
	v_cvt_pkrtz_f16_f32 v80, v39, v43
	v_cvt_pkrtz_f16_f32 v81, v47, v51
	v_cvt_pkrtz_f16_f32 v82, v55, v59
	v_cvt_pkrtz_f16_f32 v83, v63, v67
	ds_write_b128 v108, v[80:83] offset:37296
	s_waitcnt lgkmcnt(0)
	s_barrier
	ds_read_b128 v[84:87], v109 offset:36864
	ds_read_b128 v[88:91], v109 offset:46080
	ds_read_b128 v[92:95], v109 offset:55296
	ds_read_b128 v[96:99], v109 offset:64512
	s_waitcnt lgkmcnt(3)
	global_store_dwordx4 v110, v[84:87], s[2:3] nt
	s_waitcnt lgkmcnt(2)
	global_store_dwordx4 v111, v[88:91], s[2:3] nt
	s_waitcnt lgkmcnt(1)
	global_store_dwordx4 v112, v[92:95], s[2:3] nt
	s_waitcnt lgkmcnt(0)
	global_store_dwordx4 v113, v[96:99], s[2:3] nt
	s_add_u32 s2, s2, 0x80
	s_addc_u32 s3, s3, 0
